# k24 + SwiGLU epilogue: column-scale loads hoisted to the unit head (spare VGPRs), epilogue vmcnt(0) dropped so next-unit tile prefetch stays in flight
# baseline (speedup 1.0000x reference)
.LBB0_444:
	s_lshl_b32 s100, s24, 3
	s_or_b32 s100, s100, s70
	s_ashr_i32 s101, s100, 31
	s_lshl_b64 s[100:101], s[100:101], 2
	s_add_u32 s100, s26, s100
	s_addc_u32 s101, s69, s101
	global_load_dword v232, v1, s[100:101] sc1
	global_load_dword v233, v1, s[100:101] offset:16 sc1
	s_add_u32 s48, s46, 0x20080
	s_addc_u32 s49, s47, 0
	s_add_u32 s25, s50, 0x100
	s_addc_u32 s64, s51, 0
	s_mov_b32 s65, -2
	s_add_u32 s46, s48, 0xfffe0080
	s_addc_u32 s47, s49, -1
	s_add_i32 s84, 0, 0x10000
	s_cmp_eq_u32 s65, 4
	s_cselect_b32 s47, s15, s47
	s_cselect_b32 s46, s14, s46
	v_add_u32_e32 v0, s84, v147
	s_cselect_b32 s51, s17, s64
	s_cselect_b32 s50, s16, s25
	s_add_i32 s86, 0, 0x14000
	ds_read_b128 v[150:153], v0
	ds_read_b128 v[154:157], v0 offset:1024
	ds_read_b128 v[158:161], v0 offset:2048
	ds_read_b128 v[162:165], v0 offset:3072
	ds_read_b128 v[166:169], v0 offset:16384
	ds_read_b128 v[170:173], v0 offset:17408
	ds_read_b128 v[174:177], v0 offset:18432
	ds_read_b128 v[178:181], v0 offset:19456
	ds_read_b128 v[182:185], v148
	ds_read_b128 v[186:189], v148 offset:1024
	ds_read_b128 v[190:193], v148 offset:2048
	ds_read_b128 v[194:197], v148 offset:3072
	ds_read_b128 v[198:201], v148 offset:4096
	ds_read_b128 v[202:205], v148 offset:5120
	ds_read_b128 v[206:209], v148 offset:6144
	ds_read_b128 v[210:213], v148 offset:7168
	s_add_i32 m0, s59, 0xc000
	s_nop 0
	global_load_lds_dwordx4 v132, s[48:49]
	s_add_i32 m0, s59, 0xe000
	s_nop 0
	global_load_lds_dwordx4 v133, s[48:49]
	s_waitcnt vmcnt(8)
	s_waitcnt lgkmcnt(0)
	s_barrier
	s_setprio 1
	s_waitcnt lgkmcnt(0)
	v_mfma_i32_16x16x64_i8 v[126:129], v[150:153], v[182:185], 0
	v_mfma_i32_16x16x64_i8 v[122:125], v[158:161], v[182:185], 0
	v_mfma_i32_16x16x64_i8 v[110:113], v[150:153], v[190:193], 0
	v_mfma_i32_16x16x64_i8 v[106:109], v[158:161], v[190:193], 0
	v_mfma_i32_16x16x64_i8 v[94:97], v[150:153], v[198:201], 0
	v_mfma_i32_16x16x64_i8 v[90:93], v[158:161], v[198:201], 0
	v_mfma_i32_16x16x64_i8 v[78:81], v[150:153], v[206:209], 0
	v_mfma_i32_16x16x64_i8 v[74:77], v[158:161], v[206:209], 0
	v_mfma_i32_16x16x64_i8 v[126:129], v[154:157], v[186:189], v[126:129]
	v_mfma_i32_16x16x64_i8 v[122:125], v[162:165], v[186:189], v[122:125]
	v_mfma_i32_16x16x64_i8 v[110:113], v[154:157], v[194:197], v[110:113]
	v_mfma_i32_16x16x64_i8 v[106:109], v[162:165], v[194:197], v[106:109]
	v_mfma_i32_16x16x64_i8 v[94:97], v[154:157], v[202:205], v[94:97]
	v_mfma_i32_16x16x64_i8 v[90:93], v[162:165], v[202:205], v[90:93]
	v_mfma_i32_16x16x64_i8 v[78:81], v[154:157], v[210:213], v[78:81]
	v_mfma_i32_16x16x64_i8 v[74:77], v[162:165], v[210:213], v[74:77]
	s_setprio 0
	s_setprio 1
	v_mfma_i32_16x16x64_i8 v[118:121], v[166:169], v[182:185], 0
	v_mfma_i32_16x16x64_i8 v[114:117], v[174:177], v[182:185], 0
	v_mfma_i32_16x16x64_i8 v[102:105], v[166:169], v[190:193], 0
	v_mfma_i32_16x16x64_i8 v[98:101], v[174:177], v[190:193], 0
	v_mfma_i32_16x16x64_i8 v[86:89], v[166:169], v[198:201], 0
	v_mfma_i32_16x16x64_i8 v[82:85], v[174:177], v[198:201], 0
	v_mfma_i32_16x16x64_i8 v[70:73], v[166:169], v[206:209], 0
	v_mfma_i32_16x16x64_i8 v[66:69], v[174:177], v[206:209], 0
	v_mfma_i32_16x16x64_i8 v[118:121], v[170:173], v[186:189], v[118:121]
	v_mfma_i32_16x16x64_i8 v[114:117], v[178:181], v[186:189], v[114:117]
	v_mfma_i32_16x16x64_i8 v[102:105], v[170:173], v[194:197], v[102:105]
	v_mfma_i32_16x16x64_i8 v[98:101], v[178:181], v[194:197], v[98:101]
	v_mfma_i32_16x16x64_i8 v[86:89], v[170:173], v[202:205], v[86:89]
	v_mfma_i32_16x16x64_i8 v[82:85], v[178:181], v[202:205], v[82:85]
	v_mfma_i32_16x16x64_i8 v[70:73], v[170:173], v[210:213], v[70:73]
	v_mfma_i32_16x16x64_i8 v[66:69], v[178:181], v[210:213], v[66:69]
	s_setprio 0
	s_barrier
	s_add_i32 s84, s84, s40
	ds_read_b128 v[182:185], v148 offset:16384
	ds_read_b128 v[186:189], v148 offset:17408
	ds_read_b128 v[190:193], v148 offset:18432
	ds_read_b128 v[194:197], v148 offset:19456
	ds_read_b128 v[198:201], v148 offset:20480
	ds_read_b128 v[202:205], v148 offset:21504
	ds_read_b128 v[206:209], v148 offset:22528
	ds_read_b128 v[210:213], v148 offset:23552
	s_mov_b32 m0, s84
	s_nop 0
	global_load_lds_dwordx4 v143, s[50:51]
	s_add_i32 m0, s84, 0x2000
	s_add_u32 s84, s50, 0x20000
	global_load_lds_dwordx4 v144, s[50:51]
	s_addc_u32 s85, s51, 0
	s_add_i32 s86, s86, s40
	s_mov_b32 m0, s86
	s_nop 0
	global_load_lds_dwordx4 v143, s[84:85]
	s_add_i32 m0, s86, 0x2000
	s_nop 0
	global_load_lds_dwordx4 v144, s[84:85]
	s_mov_b32 m0, s59
	s_nop 0
	global_load_lds_dwordx4 v132, s[46:47]
	s_mov_b32 m0, s60
	s_nop 0
	global_load_lds_dwordx4 v133, s[46:47]
	s_waitcnt vmcnt(8)
	s_waitcnt lgkmcnt(0)
	s_barrier
	s_setprio 1
	s_waitcnt lgkmcnt(0)
	v_mfma_i32_16x16x64_i8 v[62:65], v[150:153], v[182:185], 0
	v_mfma_i32_16x16x64_i8 v[58:61], v[158:161], v[182:185], 0
	v_mfma_i32_16x16x64_i8 v[46:49], v[150:153], v[190:193], 0
	v_mfma_i32_16x16x64_i8 v[42:45], v[158:161], v[190:193], 0
	v_mfma_i32_16x16x64_i8 v[30:33], v[150:153], v[198:201], 0
	v_mfma_i32_16x16x64_i8 v[26:29], v[158:161], v[198:201], 0
	v_mfma_i32_16x16x64_i8 v[14:17], v[150:153], v[206:209], 0
	v_mfma_i32_16x16x64_i8 v[10:13], v[158:161], v[206:209], 0
	v_mfma_i32_16x16x64_i8 v[62:65], v[154:157], v[186:189], v[62:65]
	v_mfma_i32_16x16x64_i8 v[58:61], v[162:165], v[186:189], v[58:61]
	v_mfma_i32_16x16x64_i8 v[46:49], v[154:157], v[194:197], v[46:49]
	v_mfma_i32_16x16x64_i8 v[42:45], v[162:165], v[194:197], v[42:45]
	v_mfma_i32_16x16x64_i8 v[30:33], v[154:157], v[202:205], v[30:33]
	v_mfma_i32_16x16x64_i8 v[26:29], v[162:165], v[202:205], v[26:29]
	v_mfma_i32_16x16x64_i8 v[14:17], v[154:157], v[210:213], v[14:17]
	v_mfma_i32_16x16x64_i8 v[10:13], v[162:165], v[210:213], v[10:13]
	s_setprio 0
	s_setprio 1
	v_mfma_i32_16x16x64_i8 v[54:57], v[166:169], v[182:185], 0
	v_mfma_i32_16x16x64_i8 v[50:53], v[174:177], v[182:185], 0
	v_mfma_i32_16x16x64_i8 v[38:41], v[166:169], v[190:193], 0
	v_mfma_i32_16x16x64_i8 v[34:37], v[174:177], v[190:193], 0
	v_mfma_i32_16x16x64_i8 v[22:25], v[166:169], v[198:201], 0
	v_mfma_i32_16x16x64_i8 v[18:21], v[174:177], v[198:201], 0
	v_mfma_i32_16x16x64_i8 v[6:9], v[166:169], v[206:209], 0
	v_mfma_i32_16x16x64_i8 v[2:5], v[174:177], v[206:209], 0
	v_mfma_i32_16x16x64_i8 v[54:57], v[170:173], v[186:189], v[54:57]
	v_mfma_i32_16x16x64_i8 v[50:53], v[178:181], v[186:189], v[50:53]
	v_mfma_i32_16x16x64_i8 v[38:41], v[170:173], v[194:197], v[38:41]
	v_mfma_i32_16x16x64_i8 v[34:37], v[178:181], v[194:197], v[34:37]
	v_mfma_i32_16x16x64_i8 v[22:25], v[170:173], v[202:205], v[22:25]
	v_mfma_i32_16x16x64_i8 v[18:21], v[178:181], v[202:205], v[18:21]
	v_mfma_i32_16x16x64_i8 v[6:9], v[170:173], v[210:213], v[6:9]
	v_mfma_i32_16x16x64_i8 v[2:5], v[178:181], v[210:213], v[2:5]
	s_setprio 0
	s_barrier
	s_add_i32 s86, 0, 0x18000
	s_add_i32 s87, 0, 0x1c000
	ds_read_b128 v[150:153], v0 offset:32768
	ds_read_b128 v[154:157], v0 offset:33792
	ds_read_b128 v[158:161], v0 offset:34816
	ds_read_b128 v[162:165], v0 offset:35840
	ds_read_b128 v[166:169], v0 offset:49152
	ds_read_b128 v[170:173], v0 offset:50176
	ds_read_b128 v[174:177], v0 offset:51200
	ds_read_b128 v[178:181], v0 offset:52224
	s_add_u32 s84, s46, 0x20000
	s_mov_b32 m0, s61
	ds_read_b128 v[182:185], v148 offset:32768
	ds_read_b128 v[186:189], v148 offset:33792
	ds_read_b128 v[190:193], v148 offset:34816
	ds_read_b128 v[194:197], v148 offset:35840
	ds_read_b128 v[198:201], v148 offset:36864
	ds_read_b128 v[202:205], v148 offset:37888
	ds_read_b128 v[206:209], v148 offset:38912
	ds_read_b128 v[210:213], v148 offset:39936
	s_addc_u32 s85, s47, 0
	s_nop 0
	global_load_lds_dwordx4 v132, s[84:85]
	s_mov_b32 m0, s66
	s_nop 0
	global_load_lds_dwordx4 v133, s[84:85]
	s_waitcnt vmcnt(8)
	s_waitcnt lgkmcnt(0)
	s_barrier
	s_setprio 1
	s_waitcnt lgkmcnt(0)
	v_mfma_i32_16x16x64_i8 v[126:129], v[150:153], v[182:185], v[126:129]
	v_mfma_i32_16x16x64_i8 v[122:125], v[158:161], v[182:185], v[122:125]
	v_mfma_i32_16x16x64_i8 v[110:113], v[150:153], v[190:193], v[110:113]
	v_mfma_i32_16x16x64_i8 v[106:109], v[158:161], v[190:193], v[106:109]
	v_mfma_i32_16x16x64_i8 v[94:97], v[150:153], v[198:201], v[94:97]
	v_mfma_i32_16x16x64_i8 v[90:93], v[158:161], v[198:201], v[90:93]
	v_mfma_i32_16x16x64_i8 v[78:81], v[150:153], v[206:209], v[78:81]
	v_mfma_i32_16x16x64_i8 v[74:77], v[158:161], v[206:209], v[74:77]
	v_mfma_i32_16x16x64_i8 v[126:129], v[154:157], v[186:189], v[126:129]
	v_mfma_i32_16x16x64_i8 v[122:125], v[162:165], v[186:189], v[122:125]
	v_mfma_i32_16x16x64_i8 v[110:113], v[154:157], v[194:197], v[110:113]
	v_mfma_i32_16x16x64_i8 v[106:109], v[162:165], v[194:197], v[106:109]
	v_mfma_i32_16x16x64_i8 v[94:97], v[154:157], v[202:205], v[94:97]
	v_mfma_i32_16x16x64_i8 v[90:93], v[162:165], v[202:205], v[90:93]
	v_mfma_i32_16x16x64_i8 v[78:81], v[154:157], v[210:213], v[78:81]
	v_mfma_i32_16x16x64_i8 v[74:77], v[162:165], v[210:213], v[74:77]
	s_setprio 0
	s_setprio 1
	v_mfma_i32_16x16x64_i8 v[118:121], v[166:169], v[182:185], v[118:121]
	v_mfma_i32_16x16x64_i8 v[114:117], v[174:177], v[182:185], v[114:117]
	v_mfma_i32_16x16x64_i8 v[102:105], v[166:169], v[190:193], v[102:105]
	v_mfma_i32_16x16x64_i8 v[98:101], v[174:177], v[190:193], v[98:101]
	v_mfma_i32_16x16x64_i8 v[86:89], v[166:169], v[198:201], v[86:89]
	v_mfma_i32_16x16x64_i8 v[82:85], v[174:177], v[198:201], v[82:85]
	v_mfma_i32_16x16x64_i8 v[70:73], v[166:169], v[206:209], v[70:73]
	v_mfma_i32_16x16x64_i8 v[66:69], v[174:177], v[206:209], v[66:69]
	v_mfma_i32_16x16x64_i8 v[118:121], v[170:173], v[186:189], v[118:121]
	v_mfma_i32_16x16x64_i8 v[114:117], v[178:181], v[186:189], v[114:117]
	v_mfma_i32_16x16x64_i8 v[102:105], v[170:173], v[194:197], v[102:105]
	v_mfma_i32_16x16x64_i8 v[98:101], v[178:181], v[194:197], v[98:101]
	v_mfma_i32_16x16x64_i8 v[86:89], v[170:173], v[202:205], v[86:89]
	v_mfma_i32_16x16x64_i8 v[82:85], v[178:181], v[202:205], v[82:85]
	v_mfma_i32_16x16x64_i8 v[70:73], v[170:173], v[210:213], v[70:73]
	v_mfma_i32_16x16x64_i8 v[66:69], v[178:181], v[210:213], v[66:69]
	s_setprio 0
	s_barrier
	ds_read_b128 v[182:185], v148 offset:49152
	ds_read_b128 v[186:189], v148 offset:50176
	ds_read_b128 v[190:193], v148 offset:51200
	ds_read_b128 v[194:197], v148 offset:52224
	ds_read_b128 v[198:201], v148 offset:53248
	ds_read_b128 v[202:205], v148 offset:54272
	ds_read_b128 v[206:209], v148 offset:55296
	ds_read_b128 v[210:213], v148 offset:56320
	s_add_i32 s84, s86, s40
	s_add_u32 s100, s50, s38
	s_addc_u32 s101, s51, s39
	s_mov_b32 m0, s84
	s_nop 0
	global_load_lds_dwordx4 v143, s[100:101]
	s_add_i32 m0, s84, 0x2000
	s_nop 0
	s_add_u32 s50, s50, 0x20080
	s_addc_u32 s51, s51, 0
	s_add_i32 s84, s87, s40
	global_load_lds_dwordx4 v144, s[100:101]
	s_mov_b32 m0, s84
	s_nop 0
	global_load_lds_dwordx4 v143, s[50:51]
	s_add_i32 m0, s84, 0x2000
	s_nop 0
	global_load_lds_dwordx4 v144, s[50:51]
	s_mov_b32 m0, s75
	s_add_u32 s100, s46, s38
	s_addc_u32 s101, s47, s39
	v_mov_b32_e32 v0, v133
	global_load_lds_dwordx4 v132, s[100:101]
	s_mov_b32 m0, s78
	s_nop 0
	global_load_lds_dwordx4 v133, s[100:101]
	s_waitcnt vmcnt(8)
	s_waitcnt lgkmcnt(0)
	s_barrier
	s_setprio 1
	s_waitcnt lgkmcnt(0)
	v_mfma_i32_16x16x64_i8 v[62:65], v[150:153], v[182:185], v[62:65]
	v_mfma_i32_16x16x64_i8 v[58:61], v[158:161], v[182:185], v[58:61]
	v_mfma_i32_16x16x64_i8 v[46:49], v[150:153], v[190:193], v[46:49]
	v_mfma_i32_16x16x64_i8 v[42:45], v[158:161], v[190:193], v[42:45]
	v_mfma_i32_16x16x64_i8 v[30:33], v[150:153], v[198:201], v[30:33]
	v_mfma_i32_16x16x64_i8 v[26:29], v[158:161], v[198:201], v[26:29]
	v_mfma_i32_16x16x64_i8 v[14:17], v[150:153], v[206:209], v[14:17]
	v_mfma_i32_16x16x64_i8 v[10:13], v[158:161], v[206:209], v[10:13]
	v_mfma_i32_16x16x64_i8 v[62:65], v[154:157], v[186:189], v[62:65]
	v_mfma_i32_16x16x64_i8 v[58:61], v[162:165], v[186:189], v[58:61]
	v_mfma_i32_16x16x64_i8 v[46:49], v[154:157], v[194:197], v[46:49]
	v_mfma_i32_16x16x64_i8 v[42:45], v[162:165], v[194:197], v[42:45]
	v_mfma_i32_16x16x64_i8 v[30:33], v[154:157], v[202:205], v[30:33]
	v_mfma_i32_16x16x64_i8 v[26:29], v[162:165], v[202:205], v[26:29]
	v_mfma_i32_16x16x64_i8 v[14:17], v[154:157], v[210:213], v[14:17]
	v_mfma_i32_16x16x64_i8 v[10:13], v[162:165], v[210:213], v[10:13]
	s_setprio 0
	s_setprio 1
	v_mfma_i32_16x16x64_i8 v[54:57], v[166:169], v[182:185], v[54:57]
	v_mfma_i32_16x16x64_i8 v[50:53], v[174:177], v[182:185], v[50:53]
	v_mfma_i32_16x16x64_i8 v[38:41], v[166:169], v[190:193], v[38:41]
	v_mfma_i32_16x16x64_i8 v[34:37], v[174:177], v[190:193], v[34:37]
	v_mfma_i32_16x16x64_i8 v[22:25], v[166:169], v[198:201], v[22:25]
	v_mfma_i32_16x16x64_i8 v[18:21], v[174:177], v[198:201], v[18:21]
	v_mfma_i32_16x16x64_i8 v[6:9], v[166:169], v[206:209], v[6:9]
	v_mfma_i32_16x16x64_i8 v[2:5], v[174:177], v[206:209], v[2:5]
	v_mfma_i32_16x16x64_i8 v[54:57], v[170:173], v[186:189], v[54:57]
	v_mfma_i32_16x16x64_i8 v[50:53], v[178:181], v[186:189], v[50:53]
	v_mfma_i32_16x16x64_i8 v[38:41], v[170:173], v[194:197], v[38:41]
	v_mfma_i32_16x16x64_i8 v[34:37], v[178:181], v[194:197], v[34:37]
	v_mfma_i32_16x16x64_i8 v[22:25], v[170:173], v[202:205], v[22:25]
	v_mfma_i32_16x16x64_i8 v[18:21], v[178:181], v[202:205], v[18:21]
	v_mfma_i32_16x16x64_i8 v[6:9], v[170:173], v[210:213], v[6:9]
	v_mfma_i32_16x16x64_i8 v[2:5], v[178:181], v[210:213], v[2:5]
	s_setprio 0
	s_barrier
	s_add_i32 s65, s65, 2
	s_add_u32 s48, s48, 0x100
	s_addc_u32 s49, s49, 0
	s_add_u32 s25, s25, 0x100
	s_addc_u32 s64, s64, 0
	s_cmp_gt_u32 s65, 5
	s_cbranch_scc0 .LBB0_445
	s_branch .Lpeel_exit_445

.Lpeel_exit_445:
.LBB0_448:
	s_mov_b32 s100, 0xbfb8aa3b
	s_mov_b32 s101, s100
	v_mov_b32_e32 v0, v145
	v_mov_b32_e32 v130, v134
	s_lshl_b32 s25, s24, 7
	s_or_b32 s25, s25, s74
	s_mul_i32 s46, s71, 0x180000
	v_add_u32_e32 v149, s41, v130
	v_lshl_add_u32 v130, v0, 3, s25
	s_mul_hi_i32 s25, s71, 0x180000
	s_add_u32 s46, s67, s46
	s_addc_u32 s47, s68, s25
	s_lshl_b32 s24, s24, 3
	s_or_b32 s24, s24, s70
	s_ashr_i32 s25, s24, 31
	s_lshl_b64 s[24:25], s[24:25], 2
	s_add_u32 s24, s26, s24
	s_addc_u32 s25, s69, s25
	v_cvt_f32_i32_e32 v127, v127
	v_cvt_f32_i32_e32 v126, v126
	v_cvt_f32_i32_e32 v129, v129
	v_cvt_f32_i32_e32 v128, v128
	v_cvt_f32_i32_e32 v123, v123
	v_cvt_f32_i32_e32 v122, v122
	v_cvt_f32_i32_e32 v125, v125
	v_cvt_f32_i32_e32 v124, v124
	v_cvt_f32_i32_e32 v119, v119
	v_cvt_f32_i32_e32 v118, v118
	v_cvt_f32_i32_e32 v121, v121
	v_cvt_f32_i32_e32 v120, v120
	v_cvt_f32_i32_e32 v117, v117
	v_cvt_f32_i32_e32 v116, v116
	v_cvt_f32_i32_e32 v115, v115
	v_cvt_f32_i32_e32 v114, v114
	v_ashrrev_i32_e32 v131, 31, v130
	v_lshl_add_u64 v[130:131], v[130:131], 1, s[46:47]
	v_cvt_f32_i32_e32 v105, v105
	v_cvt_f32_i32_e32 v104, v104
	v_cvt_f32_i32_e32 v103, v103
	v_cvt_f32_i32_e32 v102, v102
	v_cvt_f32_i32_e32 v101, v101
	v_cvt_f32_i32_e32 v100, v100
	v_cvt_f32_i32_e32 v99, v99
	v_cvt_f32_i32_e32 v98, v98
	v_cvt_f32_i32_e32 v107, v107
	v_cvt_f32_i32_e32 v106, v106
	v_cvt_f32_i32_e32 v109, v109
	v_cvt_f32_i32_e32 v108, v108
	v_cvt_f32_i32_e32 v95, v95
	v_cvt_f32_i32_e32 v94, v94
	v_cvt_f32_i32_e32 v97, v97
	v_cvt_f32_i32_e32 v96, v96
	v_cvt_f32_i32_e32 v91, v91
	v_cvt_f32_i32_e32 v90, v90
	v_cvt_f32_i32_e32 v93, v93
	v_cvt_f32_i32_e32 v92, v92
	v_cvt_f32_i32_e32 v87, v87
	v_cvt_f32_i32_e32 v86, v86
	v_cvt_f32_i32_e32 v89, v89
	v_cvt_f32_i32_e32 v88, v88
	v_cvt_f32_i32_e32 v79, v79
	v_cvt_f32_i32_e32 v78, v78
	v_cvt_f32_i32_e32 v81, v81
	v_cvt_f32_i32_e32 v80, v80
	v_cvt_f32_i32_e32 v75, v75
	v_cvt_f32_i32_e32 v74, v74
	v_cvt_f32_i32_e32 v77, v77
	v_cvt_f32_i32_e32 v76, v76
	v_cvt_f32_i32_e32 v85, v85
	v_cvt_f32_i32_e32 v84, v84
	v_cvt_f32_i32_e32 v83, v83
	v_cvt_f32_i32_e32 v82, v82
	v_cvt_f32_i32_e32 v71, v71
	v_cvt_f32_i32_e32 v70, v70
	v_cvt_f32_i32_e32 v73, v73
	v_cvt_f32_i32_e32 v72, v72
	v_cvt_f32_i32_e32 v63, v63
	v_cvt_f32_i32_e32 v62, v62
	v_cvt_f32_i32_e32 v65, v65
	v_cvt_f32_i32_e32 v64, v64
	v_cvt_f32_i32_e32 v59, v59
	v_cvt_f32_i32_e32 v58, v58
	v_cvt_f32_i32_e32 v61, v61
	v_cvt_f32_i32_e32 v60, v60
	v_cvt_f32_i32_e32 v69, v69
	v_cvt_f32_i32_e32 v68, v68
	v_cvt_f32_i32_e32 v67, v67
	v_cvt_f32_i32_e32 v66, v66
	v_cvt_f32_i32_e32 v55, v55
	v_cvt_f32_i32_e32 v54, v54
	v_cvt_f32_i32_e32 v57, v57
	v_cvt_f32_i32_e32 v56, v56
	v_cvt_f32_i32_e32 v47, v47
	v_cvt_f32_i32_e32 v46, v46
	v_cvt_f32_i32_e32 v49, v49
	v_cvt_f32_i32_e32 v48, v48
	s_and_b64 vcc, exec, s[10:11]
	s_cbranch_vccz .Lepi_lead_448
	s_barrier
.Lepi_lead_448:
	v_mul_f32_e32 v0, v135, v232
	v_pk_mul_f32 v[126:127], v[0:1], v[126:127] op_sel_hi:[0,1]
	v_pk_mul_f32 v[128:129], v[0:1], v[128:129] op_sel_hi:[0,1]
	v_pk_mul_f32 v[124:125], v[0:1], v[124:125] op_sel_hi:[0,1]
	v_pk_mul_f32 v[122:123], v[0:1], v[122:123] op_sel_hi:[0,1]
	v_pk_mul_f32 v[214:215], v[126:127], s[100:101] op_sel_hi:[1,0]
	v_exp_f32_e32 v214, v214
	v_exp_f32_e32 v215, v215
	v_mul_f32_e32 v152, v135, v233
	v_pk_mul_f32 v[118:119], v[152:153], v[118:119] op_sel_hi:[0,1]
	v_pk_mul_f32 v[120:121], v[152:153], v[120:121] op_sel_hi:[0,1]
	v_pk_add_f32 v[214:215], v[214:215], 1.0 op_sel_hi:[1,0]
	v_rcp_f32_e32 v154, v214
	v_pk_mul_f32 v[114:115], v[152:153], v[114:115] op_sel_hi:[0,1]
	v_pk_mul_f32 v[116:117], v[152:153], v[116:117] op_sel_hi:[0,1]
	v_mad_i64_i32 v[152:153], s[24:25], v149, s52, v[130:131]
	v_rcp_f32_e32 v155, v215
	v_pk_mul_f32 v[216:217], v[128:129], s[100:101] op_sel_hi:[1,0]
	v_exp_f32_e32 v216, v216
	v_exp_f32_e32 v217, v217
	v_cvt_f32_i32_e32 v43, v43
	v_pk_mul_f32 v[126:127], v[126:127], v[154:155]
	v_cvt_f32_i32_e32 v42, v42
	v_pk_add_f32 v[216:217], v[216:217], 1.0 op_sel_hi:[1,0]
	v_rcp_f32_e32 v156, v216
	v_pk_mul_f32 v[118:119], v[118:119], v[126:127]
	v_cvt_f32_i32_e32 v45, v45
	v_cvt_f32_i32_e32 v44, v44
	v_rcp_f32_e32 v157, v217
	v_pk_mul_f32 v[218:219], v[122:123], s[100:101] op_sel_hi:[1,0]
	v_exp_f32_e32 v218, v218
	v_exp_f32_e32 v219, v219
	v_cvt_f32_i32_e32 v53, v53
	v_pk_mul_f32 v[128:129], v[128:129], v[156:157]
	v_cvt_f32_i32_e32 v52, v52
	v_pk_add_f32 v[218:219], v[218:219], 1.0 op_sel_hi:[1,0]
	v_rcp_f32_e32 v126, v218
	v_pk_mul_f32 v[120:121], v[120:121], v[128:129]
	v_cvt_f32_i32_e32 v51, v51
	v_cvt_f32_i32_e32 v50, v50
	v_rcp_f32_e32 v127, v219
	v_pk_mul_f32 v[220:221], v[124:125], s[100:101] op_sel_hi:[1,0]
	v_exp_f32_e32 v220, v220
	v_exp_f32_e32 v221, v221
	v_cvt_f32_i32_e32 v39, v39
	v_pk_mul_f32 v[122:123], v[122:123], v[126:127]
	v_cvt_f32_i32_e32 v38, v38
	v_pk_add_f32 v[220:221], v[220:221], 1.0 op_sel_hi:[1,0]
	v_rcp_f32_e32 v128, v220
	v_cvt_f32_i32_e32 v41, v41
	v_cvt_f32_i32_e32 v40, v40
	v_cvt_f32_i32_e32 v31, v31
	v_rcp_f32_e32 v129, v221
	v_mul_f32_e32 v0, v136, v233
	v_pk_mul_f32 v[102:103], v[0:1], v[102:103] op_sel_hi:[0,1]
	v_pk_mul_f32 v[104:105], v[0:1], v[104:105] op_sel_hi:[0,1]
	v_pk_mul_f32 v[124:125], v[124:125], v[128:129]
	v_pk_mul_f32 v[98:99], v[0:1], v[98:99] op_sel_hi:[0,1]
	v_pk_mul_f32 v[124:125], v[116:117], v[124:125]
	v_pk_mul_f32 v[116:117], v[114:115], v[122:123]
	v_cvt_pk_bf16_f32 v114, v118, v119
	v_cvt_pk_bf16_f32 v115, v120, v121
	v_pk_mul_f32 v[100:101], v[0:1], v[100:101] op_sel_hi:[0,1]
	v_cvt_pk_bf16_f32 v116, v116, v117
	v_cvt_pk_bf16_f32 v117, v124, v125
	global_store_dwordx4 v[152:153], v[114:117], off
	v_cvt_f32_i32_e32 v30, v30
	v_cvt_f32_i32_e32 v33, v33
	v_cvt_f32_i32_e32 v117, v111
	v_cvt_f32_i32_e32 v116, v110
	v_add_u32_e32 v115, 16, v149
	v_mul_f32_e32 v114, v136, v232
	v_cvt_f32_i32_e32 v111, v113
	v_cvt_f32_i32_e32 v110, v112
	v_pk_mul_f32 v[112:113], v[114:115], v[116:117] op_sel_hi:[0,1]
	v_pk_mul_f32 v[222:223], v[112:113], s[100:101] op_sel_hi:[1,0]
	v_exp_f32_e32 v222, v222
	v_exp_f32_e32 v223, v223
	v_pk_mul_f32 v[110:111], v[114:115], v[110:111] op_sel_hi:[0,1]
	v_pk_mul_f32 v[106:107], v[114:115], v[106:107] op_sel_hi:[0,1]
	v_pk_mul_f32 v[108:109], v[114:115], v[108:109] op_sel_hi:[0,1]
	v_pk_add_f32 v[222:223], v[222:223], 1.0 op_sel_hi:[1,0]
	v_rcp_f32_e32 v116, v222
	v_mad_i64_i32 v[114:115], s[24:25], v115, s52, v[130:131]
	v_cvt_f32_i32_e32 v32, v32
	v_rcp_f32_e32 v117, v223
	v_pk_mul_f32 v[224:225], v[110:111], s[100:101] op_sel_hi:[1,0]
	v_exp_f32_e32 v224, v224
	v_exp_f32_e32 v225, v225
	v_cvt_f32_i32_e32 v27, v27
	v_pk_mul_f32 v[112:113], v[112:113], v[116:117]
	v_cvt_f32_i32_e32 v26, v26
	v_pk_add_f32 v[224:225], v[224:225], 1.0 op_sel_hi:[1,0]
	v_rcp_f32_e32 v118, v224
	v_pk_mul_f32 v[102:103], v[102:103], v[112:113]
	v_cvt_f32_i32_e32 v29, v29
	v_cvt_f32_i32_e32 v28, v28
	v_rcp_f32_e32 v119, v225
	v_pk_mul_f32 v[226:227], v[106:107], s[100:101] op_sel_hi:[1,0]
	v_exp_f32_e32 v226, v226
	v_exp_f32_e32 v227, v227
	v_cvt_f32_i32_e32 v37, v37
	v_pk_mul_f32 v[110:111], v[110:111], v[118:119]
	v_cvt_f32_i32_e32 v36, v36
	v_pk_add_f32 v[226:227], v[226:227], 1.0 op_sel_hi:[1,0]
	v_pk_mul_f32 v[104:105], v[104:105], v[110:111]
	v_rcp_f32_e32 v110, v226
	v_cvt_f32_i32_e32 v35, v35
	v_cvt_f32_i32_e32 v34, v34
	v_cvt_f32_i32_e32 v23, v23
	v_rcp_f32_e32 v111, v227
	v_pk_mul_f32 v[228:229], v[108:109], s[100:101] op_sel_hi:[1,0]
	v_exp_f32_e32 v228, v228
	v_exp_f32_e32 v229, v229
	v_cvt_f32_i32_e32 v22, v22
	v_pk_mul_f32 v[106:107], v[106:107], v[110:111]
	v_cvt_f32_i32_e32 v25, v25
	v_pk_add_f32 v[228:229], v[228:229], 1.0 op_sel_hi:[1,0]
	v_rcp_f32_e32 v112, v228
	v_cvt_f32_i32_e32 v24, v24
	v_cvt_f32_i32_e32 v15, v15
	v_cvt_f32_i32_e32 v14, v14
	v_rcp_f32_e32 v113, v229
	v_mul_f32_e32 v0, v137, v232
	v_pk_mul_f32 v[94:95], v[0:1], v[94:95] op_sel_hi:[0,1]
	v_pk_mul_f32 v[96:97], v[0:1], v[96:97] op_sel_hi:[0,1]
	v_pk_mul_f32 v[92:93], v[0:1], v[92:93] op_sel_hi:[0,1]
	v_pk_mul_f32 v[90:91], v[0:1], v[90:91] op_sel_hi:[0,1]
	v_pk_mul_f32 v[214:215], v[94:95], s[100:101] op_sel_hi:[1,0]
	v_exp_f32_e32 v214, v214
	v_exp_f32_e32 v215, v215
	v_pk_mul_f32 v[108:109], v[108:109], v[112:113]
	v_cvt_f32_i32_e32 v17, v17
	v_pk_mul_f32 v[108:109], v[100:101], v[108:109]
	v_pk_mul_f32 v[100:101], v[98:99], v[106:107]
	v_cvt_pk_bf16_f32 v98, v102, v103
	v_cvt_pk_bf16_f32 v99, v104, v105
	v_pk_add_f32 v[214:215], v[214:215], 1.0 op_sel_hi:[1,0]
	v_cvt_pk_bf16_f32 v100, v100, v101
	v_cvt_pk_bf16_f32 v101, v108, v109
	global_store_dwordx4 v[114:115], v[98:101], off
	v_cvt_f32_i32_e32 v16, v16
	v_cvt_f32_i32_e32 v11, v11
	v_rcp_f32_e32 v100, v214
	v_add_u32_e32 v99, 32, v149
	v_mul_f32_e32 v98, v137, v233
	v_pk_mul_f32 v[86:87], v[98:99], v[86:87] op_sel_hi:[0,1]
	v_rcp_f32_e32 v101, v215
	v_pk_mul_f32 v[216:217], v[96:97], s[100:101] op_sel_hi:[1,0]
	v_exp_f32_e32 v216, v216
	v_exp_f32_e32 v217, v217
	v_pk_mul_f32 v[88:89], v[98:99], v[88:89] op_sel_hi:[0,1]
	v_pk_mul_f32 v[94:95], v[94:95], v[100:101]
	v_pk_mul_f32 v[82:83], v[98:99], v[82:83] op_sel_hi:[0,1]
	v_pk_add_f32 v[216:217], v[216:217], 1.0 op_sel_hi:[1,0]
	v_rcp_f32_e32 v102, v216
	v_pk_mul_f32 v[86:87], v[86:87], v[94:95]
	v_pk_mul_f32 v[84:85], v[98:99], v[84:85] op_sel_hi:[0,1]
	v_mad_i64_i32 v[98:99], s[24:25], v99, s52, v[130:131]
	v_rcp_f32_e32 v103, v217
	v_pk_mul_f32 v[218:219], v[90:91], s[100:101] op_sel_hi:[1,0]
	v_exp_f32_e32 v218, v218
	v_exp_f32_e32 v219, v219
	v_cvt_f32_i32_e32 v10, v10
	v_pk_mul_f32 v[96:97], v[96:97], v[102:103]
	v_cvt_f32_i32_e32 v13, v13
	v_pk_add_f32 v[218:219], v[218:219], 1.0 op_sel_hi:[1,0]
	v_rcp_f32_e32 v94, v218
	v_pk_mul_f32 v[88:89], v[88:89], v[96:97]
	v_cvt_f32_i32_e32 v12, v12
	v_cvt_f32_i32_e32 v21, v21
	v_rcp_f32_e32 v95, v219
	v_pk_mul_f32 v[220:221], v[92:93], s[100:101] op_sel_hi:[1,0]
	v_exp_f32_e32 v220, v220
	v_exp_f32_e32 v221, v221
	v_cvt_f32_i32_e32 v20, v20
	v_pk_mul_f32 v[90:91], v[90:91], v[94:95]
	v_cvt_f32_i32_e32 v19, v19
	v_pk_add_f32 v[220:221], v[220:221], 1.0 op_sel_hi:[1,0]
	v_rcp_f32_e32 v96, v220
	v_cvt_f32_i32_e32 v18, v18
	v_cvt_f32_i32_e32 v7, v7
	v_cvt_f32_i32_e32 v6, v6
	v_rcp_f32_e32 v97, v221
	v_mul_f32_e32 v0, v138, v232
	v_pk_mul_f32 v[78:79], v[0:1], v[78:79] op_sel_hi:[0,1]
	v_pk_mul_f32 v[80:81], v[0:1], v[80:81] op_sel_hi:[0,1]
	v_pk_mul_f32 v[76:77], v[0:1], v[76:77] op_sel_hi:[0,1]
	v_pk_mul_f32 v[74:75], v[0:1], v[74:75] op_sel_hi:[0,1]
	v_pk_mul_f32 v[222:223], v[78:79], s[100:101] op_sel_hi:[1,0]
	v_exp_f32_e32 v222, v222
	v_exp_f32_e32 v223, v223
	v_pk_mul_f32 v[92:93], v[92:93], v[96:97]
	v_cvt_f32_i32_e32 v9, v9
	v_pk_mul_f32 v[92:93], v[84:85], v[92:93]
	v_pk_mul_f32 v[84:85], v[82:83], v[90:91]
	v_cvt_pk_bf16_f32 v82, v86, v87
	v_cvt_pk_bf16_f32 v83, v88, v89
	v_pk_add_f32 v[222:223], v[222:223], 1.0 op_sel_hi:[1,0]
	v_cvt_pk_bf16_f32 v84, v84, v85
	v_cvt_pk_bf16_f32 v85, v92, v93
	global_store_dwordx4 v[98:99], v[82:85], off
	v_cvt_f32_i32_e32 v8, v8
	v_cvt_f32_i32_e32 v5, v5
	v_rcp_f32_e32 v84, v222
	v_add_u32_e32 v83, 48, v149
	v_mul_f32_e32 v82, v138, v233
	v_pk_mul_f32 v[70:71], v[82:83], v[70:71] op_sel_hi:[0,1]
	v_rcp_f32_e32 v85, v223
	v_pk_mul_f32 v[224:225], v[80:81], s[100:101] op_sel_hi:[1,0]
	v_exp_f32_e32 v224, v224
	v_exp_f32_e32 v225, v225
	v_pk_mul_f32 v[72:73], v[82:83], v[72:73] op_sel_hi:[0,1]
	v_pk_mul_f32 v[78:79], v[78:79], v[84:85]
	v_pk_mul_f32 v[66:67], v[82:83], v[66:67] op_sel_hi:[0,1]
	v_pk_add_f32 v[224:225], v[224:225], 1.0 op_sel_hi:[1,0]
	v_rcp_f32_e32 v86, v224
	v_pk_mul_f32 v[70:71], v[70:71], v[78:79]
	v_pk_mul_f32 v[68:69], v[82:83], v[68:69] op_sel_hi:[0,1]
	v_mad_i64_i32 v[82:83], s[24:25], v83, s52, v[130:131]
	v_rcp_f32_e32 v87, v225
	v_pk_mul_f32 v[226:227], v[74:75], s[100:101] op_sel_hi:[1,0]
	v_exp_f32_e32 v226, v226
	v_exp_f32_e32 v227, v227
	v_cvt_f32_i32_e32 v4, v4
	v_pk_mul_f32 v[80:81], v[80:81], v[86:87]
	v_cvt_f32_i32_e32 v3, v3
	v_pk_add_f32 v[226:227], v[226:227], 1.0 op_sel_hi:[1,0]
	v_rcp_f32_e32 v78, v226
	v_pk_mul_f32 v[72:73], v[72:73], v[80:81]
	v_cvt_f32_i32_e32 v2, v2
	s_andn2_b64 vcc, exec, s[22:23]
	v_rcp_f32_e32 v79, v227
	v_pk_mul_f32 v[228:229], v[76:77], s[100:101] op_sel_hi:[1,0]
	v_exp_f32_e32 v228, v228
	v_exp_f32_e32 v229, v229
	v_pk_mul_f32 v[74:75], v[74:75], v[78:79]
	v_pk_add_f32 v[228:229], v[228:229], 1.0 op_sel_hi:[1,0]
	v_rcp_f32_e32 v80, v228
	s_nop 0
	v_rcp_f32_e32 v81, v229
	v_mul_f32_e32 v0, v139, v232
	v_pk_mul_f32 v[62:63], v[0:1], v[62:63] op_sel_hi:[0,1]
	v_pk_mul_f32 v[64:65], v[0:1], v[64:65] op_sel_hi:[0,1]
	v_pk_mul_f32 v[60:61], v[0:1], v[60:61] op_sel_hi:[0,1]
	v_pk_mul_f32 v[58:59], v[0:1], v[58:59] op_sel_hi:[0,1]
	v_pk_mul_f32 v[214:215], v[62:63], s[100:101] op_sel_hi:[1,0]
	v_exp_f32_e32 v214, v214
	v_exp_f32_e32 v215, v215
	v_pk_mul_f32 v[76:77], v[76:77], v[80:81]
	v_pk_add_f32 v[214:215], v[214:215], 1.0 op_sel_hi:[1,0]
	v_pk_mul_f32 v[76:77], v[68:69], v[76:77]
	v_pk_mul_f32 v[68:69], v[66:67], v[74:75]
	v_cvt_pk_bf16_f32 v66, v70, v71
	v_cvt_pk_bf16_f32 v67, v72, v73
	s_nop 0
	v_cvt_pk_bf16_f32 v68, v68, v69
	v_cvt_pk_bf16_f32 v69, v76, v77
	global_store_dwordx4 v[82:83], v[66:69], off
	s_nop 1
	v_rcp_f32_e32 v68, v214
	v_add_u32_e32 v67, 0x80, v149
	v_mul_f32_e32 v66, v139, v233
	v_pk_mul_f32 v[54:55], v[66:67], v[54:55] op_sel_hi:[0,1]
	v_rcp_f32_e32 v69, v215
	v_pk_mul_f32 v[216:217], v[64:65], s[100:101] op_sel_hi:[1,0]
	v_exp_f32_e32 v216, v216
	v_exp_f32_e32 v217, v217
	v_pk_mul_f32 v[56:57], v[66:67], v[56:57] op_sel_hi:[0,1]
	v_pk_mul_f32 v[62:63], v[62:63], v[68:69]
	v_pk_mul_f32 v[50:51], v[66:67], v[50:51] op_sel_hi:[0,1]
	v_pk_add_f32 v[216:217], v[216:217], 1.0 op_sel_hi:[1,0]
	v_rcp_f32_e32 v70, v216
	v_pk_mul_f32 v[54:55], v[54:55], v[62:63]
	v_pk_mul_f32 v[52:53], v[66:67], v[52:53] op_sel_hi:[0,1]
	v_mad_i64_i32 v[66:67], s[24:25], v67, s52, v[130:131]
	v_rcp_f32_e32 v71, v217
	v_pk_mul_f32 v[218:219], v[58:59], s[100:101] op_sel_hi:[1,0]
	v_exp_f32_e32 v218, v218
	v_exp_f32_e32 v219, v219
	v_pk_mul_f32 v[64:65], v[64:65], v[70:71]
	s_nop 0
	v_pk_mul_f32 v[56:57], v[56:57], v[64:65]
	v_pk_add_f32 v[218:219], v[218:219], 1.0 op_sel_hi:[1,0]
	v_rcp_f32_e32 v62, v218
	s_nop 0
	v_rcp_f32_e32 v63, v219
	v_pk_mul_f32 v[220:221], v[60:61], s[100:101] op_sel_hi:[1,0]
	v_exp_f32_e32 v220, v220
	v_exp_f32_e32 v221, v221
	v_pk_mul_f32 v[58:59], v[58:59], v[62:63]
	v_pk_add_f32 v[220:221], v[220:221], 1.0 op_sel_hi:[1,0]
	v_rcp_f32_e32 v64, v220
	s_nop 0
	v_rcp_f32_e32 v65, v221
	v_mul_f32_e32 v0, v140, v232
	v_pk_mul_f32 v[46:47], v[0:1], v[46:47] op_sel_hi:[0,1]
	v_pk_mul_f32 v[48:49], v[0:1], v[48:49] op_sel_hi:[0,1]
	v_pk_mul_f32 v[44:45], v[0:1], v[44:45] op_sel_hi:[0,1]
	v_pk_mul_f32 v[42:43], v[0:1], v[42:43] op_sel_hi:[0,1]
	v_pk_mul_f32 v[222:223], v[46:47], s[100:101] op_sel_hi:[1,0]
	v_exp_f32_e32 v222, v222
	v_exp_f32_e32 v223, v223
	v_pk_mul_f32 v[60:61], v[60:61], v[64:65]
	v_pk_add_f32 v[222:223], v[222:223], 1.0 op_sel_hi:[1,0]
	v_pk_mul_f32 v[60:61], v[52:53], v[60:61]
	v_pk_mul_f32 v[52:53], v[50:51], v[58:59]
	v_cvt_pk_bf16_f32 v50, v54, v55
	v_cvt_pk_bf16_f32 v51, v56, v57
	s_nop 0
	v_cvt_pk_bf16_f32 v52, v52, v53
	v_cvt_pk_bf16_f32 v53, v60, v61
	global_store_dwordx4 v[66:67], v[50:53], off
	s_nop 1
	v_rcp_f32_e32 v52, v222
	v_add_u32_e32 v51, 0x90, v149
	v_mul_f32_e32 v50, v140, v233
	v_pk_mul_f32 v[38:39], v[50:51], v[38:39] op_sel_hi:[0,1]
	v_rcp_f32_e32 v53, v223
	v_pk_mul_f32 v[224:225], v[48:49], s[100:101] op_sel_hi:[1,0]
	v_exp_f32_e32 v224, v224
	v_exp_f32_e32 v225, v225
	v_pk_mul_f32 v[40:41], v[50:51], v[40:41] op_sel_hi:[0,1]
	v_pk_mul_f32 v[46:47], v[46:47], v[52:53]
	v_pk_mul_f32 v[34:35], v[50:51], v[34:35] op_sel_hi:[0,1]
	v_pk_add_f32 v[224:225], v[224:225], 1.0 op_sel_hi:[1,0]
	v_rcp_f32_e32 v54, v224
	v_pk_mul_f32 v[38:39], v[38:39], v[46:47]
	v_pk_mul_f32 v[36:37], v[50:51], v[36:37] op_sel_hi:[0,1]
	v_mad_i64_i32 v[50:51], s[24:25], v51, s52, v[130:131]
	v_rcp_f32_e32 v55, v225
	v_pk_mul_f32 v[226:227], v[42:43], s[100:101] op_sel_hi:[1,0]
	v_exp_f32_e32 v226, v226
	v_exp_f32_e32 v227, v227
	v_pk_mul_f32 v[48:49], v[48:49], v[54:55]
	s_nop 0
	v_pk_mul_f32 v[40:41], v[40:41], v[48:49]
	v_pk_add_f32 v[226:227], v[226:227], 1.0 op_sel_hi:[1,0]
	v_rcp_f32_e32 v46, v226
	s_nop 0
	v_rcp_f32_e32 v47, v227
	v_pk_mul_f32 v[228:229], v[44:45], s[100:101] op_sel_hi:[1,0]
	v_exp_f32_e32 v228, v228
	v_exp_f32_e32 v229, v229
	v_pk_mul_f32 v[42:43], v[42:43], v[46:47]
	v_pk_add_f32 v[228:229], v[228:229], 1.0 op_sel_hi:[1,0]
	v_rcp_f32_e32 v48, v228
	s_nop 0
	v_rcp_f32_e32 v49, v229
	v_mul_f32_e32 v0, v141, v232
	v_pk_mul_f32 v[30:31], v[0:1], v[30:31] op_sel_hi:[0,1]
	v_pk_mul_f32 v[32:33], v[0:1], v[32:33] op_sel_hi:[0,1]
	v_pk_mul_f32 v[28:29], v[0:1], v[28:29] op_sel_hi:[0,1]
	v_pk_mul_f32 v[26:27], v[0:1], v[26:27] op_sel_hi:[0,1]
	v_pk_mul_f32 v[214:215], v[30:31], s[100:101] op_sel_hi:[1,0]
	v_exp_f32_e32 v214, v214
	v_exp_f32_e32 v215, v215
	v_pk_mul_f32 v[44:45], v[44:45], v[48:49]
	v_pk_add_f32 v[214:215], v[214:215], 1.0 op_sel_hi:[1,0]
	v_pk_mul_f32 v[44:45], v[36:37], v[44:45]
	v_pk_mul_f32 v[36:37], v[34:35], v[42:43]
	v_cvt_pk_bf16_f32 v34, v38, v39
	v_cvt_pk_bf16_f32 v35, v40, v41
	s_nop 0
	v_cvt_pk_bf16_f32 v36, v36, v37
	v_cvt_pk_bf16_f32 v37, v44, v45
	global_store_dwordx4 v[50:51], v[34:37], off
	s_nop 1
	v_rcp_f32_e32 v36, v214
	v_add_u32_e32 v35, 0xa0, v149
	v_mul_f32_e32 v34, v141, v233
	v_pk_mul_f32 v[22:23], v[34:35], v[22:23] op_sel_hi:[0,1]
	v_rcp_f32_e32 v37, v215
	v_pk_mul_f32 v[216:217], v[32:33], s[100:101] op_sel_hi:[1,0]
	v_exp_f32_e32 v216, v216
	v_exp_f32_e32 v217, v217
	v_pk_mul_f32 v[24:25], v[34:35], v[24:25] op_sel_hi:[0,1]
	v_pk_mul_f32 v[30:31], v[30:31], v[36:37]
	v_pk_mul_f32 v[18:19], v[34:35], v[18:19] op_sel_hi:[0,1]
	v_pk_add_f32 v[216:217], v[216:217], 1.0 op_sel_hi:[1,0]
	v_rcp_f32_e32 v38, v216
	v_pk_mul_f32 v[22:23], v[22:23], v[30:31]
	v_pk_mul_f32 v[20:21], v[34:35], v[20:21] op_sel_hi:[0,1]
	v_mad_i64_i32 v[34:35], s[24:25], v35, s52, v[130:131]
	v_rcp_f32_e32 v39, v217
	v_pk_mul_f32 v[218:219], v[26:27], s[100:101] op_sel_hi:[1,0]
	v_exp_f32_e32 v218, v218
	v_exp_f32_e32 v219, v219
	v_pk_mul_f32 v[32:33], v[32:33], v[38:39]
	s_nop 0
	v_pk_mul_f32 v[24:25], v[24:25], v[32:33]
	v_pk_add_f32 v[218:219], v[218:219], 1.0 op_sel_hi:[1,0]
	v_rcp_f32_e32 v30, v218
	s_nop 0
	v_rcp_f32_e32 v31, v219
	v_pk_mul_f32 v[220:221], v[28:29], s[100:101] op_sel_hi:[1,0]
	v_exp_f32_e32 v220, v220
	v_exp_f32_e32 v221, v221
	v_pk_mul_f32 v[26:27], v[26:27], v[30:31]
	v_pk_add_f32 v[220:221], v[220:221], 1.0 op_sel_hi:[1,0]
	v_rcp_f32_e32 v32, v220
	s_nop 0
	v_rcp_f32_e32 v33, v221
	v_mul_f32_e32 v0, v142, v232
	v_pk_mul_f32 v[14:15], v[0:1], v[14:15] op_sel_hi:[0,1]
	v_pk_mul_f32 v[16:17], v[0:1], v[16:17] op_sel_hi:[0,1]
	v_pk_mul_f32 v[12:13], v[0:1], v[12:13] op_sel_hi:[0,1]
	v_pk_mul_f32 v[10:11], v[0:1], v[10:11] op_sel_hi:[0,1]
	v_pk_mul_f32 v[222:223], v[14:15], s[100:101] op_sel_hi:[1,0]
	v_exp_f32_e32 v222, v222
	v_exp_f32_e32 v223, v223
	v_pk_mul_f32 v[28:29], v[28:29], v[32:33]
	v_pk_add_f32 v[222:223], v[222:223], 1.0 op_sel_hi:[1,0]
	v_pk_mul_f32 v[28:29], v[20:21], v[28:29]
	v_pk_mul_f32 v[20:21], v[18:19], v[26:27]
	v_cvt_pk_bf16_f32 v18, v22, v23
	v_cvt_pk_bf16_f32 v19, v24, v25
	s_nop 0
	v_cvt_pk_bf16_f32 v20, v20, v21
	v_cvt_pk_bf16_f32 v21, v28, v29
	global_store_dwordx4 v[34:35], v[18:21], off
	s_nop 1
	v_rcp_f32_e32 v20, v222
	v_add_u32_e32 v19, 0xb0, v149
	v_mul_f32_e32 v18, v142, v233
	v_pk_mul_f32 v[6:7], v[18:19], v[6:7] op_sel_hi:[0,1]
	v_rcp_f32_e32 v21, v223
	v_pk_mul_f32 v[224:225], v[16:17], s[100:101] op_sel_hi:[1,0]
	v_exp_f32_e32 v224, v224
	v_exp_f32_e32 v225, v225
	v_pk_mul_f32 v[8:9], v[18:19], v[8:9] op_sel_hi:[0,1]
	v_pk_mul_f32 v[14:15], v[14:15], v[20:21]
	v_pk_mul_f32 v[2:3], v[18:19], v[2:3] op_sel_hi:[0,1]
	v_pk_add_f32 v[224:225], v[224:225], 1.0 op_sel_hi:[1,0]
	v_rcp_f32_e32 v22, v224
	v_pk_mul_f32 v[6:7], v[6:7], v[14:15]
	v_pk_mul_f32 v[4:5], v[18:19], v[4:5] op_sel_hi:[0,1]
	v_mad_i64_i32 v[18:19], s[24:25], v19, s52, v[130:131]
	v_rcp_f32_e32 v23, v225
	v_pk_mul_f32 v[226:227], v[10:11], s[100:101] op_sel_hi:[1,0]
	v_exp_f32_e32 v226, v226
	v_exp_f32_e32 v227, v227
	s_mov_b64 s[24:25], -1
	v_pk_mul_f32 v[16:17], v[16:17], v[22:23]
	v_pk_add_f32 v[226:227], v[226:227], 1.0 op_sel_hi:[1,0]
	v_rcp_f32_e32 v14, v226
	v_pk_mul_f32 v[8:9], v[8:9], v[16:17]
	v_rcp_f32_e32 v15, v227
	v_pk_mul_f32 v[228:229], v[12:13], s[100:101] op_sel_hi:[1,0]
	v_exp_f32_e32 v228, v228
	v_exp_f32_e32 v229, v229
	v_pk_mul_f32 v[10:11], v[10:11], v[14:15]
	v_pk_add_f32 v[228:229], v[228:229], 1.0 op_sel_hi:[1,0]
	v_rcp_f32_e32 v16, v228
	s_nop 0
	v_rcp_f32_e32 v17, v229
	s_nop 0
	v_pk_mul_f32 v[12:13], v[12:13], v[16:17]
	s_nop 0
	v_pk_mul_f32 v[12:13], v[4:5], v[12:13]
	v_pk_mul_f32 v[4:5], v[2:3], v[10:11]
	v_cvt_pk_bf16_f32 v2, v6, v7
	v_cvt_pk_bf16_f32 v3, v8, v9
	s_nop 0
	v_cvt_pk_bf16_f32 v4, v4, v5
	v_cvt_pk_bf16_f32 v5, v12, v13
	global_store_dwordx4 v[18:19], v[2:5], off
	s_cbranch_vccnz .LBB0_441
	s_cmp_eq_u32 s83, s71
	s_cbranch_scc1 .LBB0_451
	v_lshl_add_u32 v2, s83, 8, v146
	v_ashrrev_i32_e32 v3, 31, v2
	v_lshl_add_u64 v[2:3], v[2:3], 2, s[4:5]
	global_load_dword v135, v[2:3], off sc1
	global_load_dword v136, v[2:3], off offset:64 sc1
	global_load_dword v137, v[2:3], off offset:128 sc1
	global_load_dword v138, v[2:3], off offset:192 sc1
	global_load_dword v139, v[2:3], off offset:512 sc1
	global_load_dword v140, v[2:3], off offset:576 sc1
	global_load_dword v141, v[2:3], off offset:640 sc1
	global_load_dword v142, v[2:3], off offset:704 sc1
